# v23a: v18 with the E/F/G K-loop heads aligned to 256 bytes (.p2align 8)
# speedup vs baseline: 1.0069x; 1.0069x over previous
; template <class Epi, class Sched, bool ALIGN_EPI = false, bool SP2 = false>
; __device__ __forceinline__ void gemm_phase(PG8_LAS unsigned char* lds, const Gemm g, const Sched& S, const Epi& E) {
;     ...
;     for (;;) {
;         const bool has_next = S.next(ui + 1, nxt);
;         const char* nA = has_next ? (const char*)g.A + (size_t)nxt.pm * tstep : cA; const char* nB = has_next ? (const char*)g.Bt + (size_t)nxt.pn * tstep : cB;
;         for (int t = 0; t < nt; t += 2) {
;             const bool last = (t == nt - 2);
;             const char* a1 = cA + (size_t)(t + 1) * kstep;
;             const char* a2 = last ? nA : cA + (size_t)(t + 2) * kstep; const char* b2 = last ? nB : cB + (size_t)(t + 2) * kstep;
;             const char* a3 = a2 + kstep; const char* b3 = b2 + kstep;
;     ...
; #pragma unroll
;         for (int a = 0; a < 2; ++a)
; #pragma unroll
;             for (int b = 0; b < 2; ++b)
; #pragma unroll
;                 for (int m = 0; m < 4; ++m)
; #pragma unroll
;                     for (int n = 0; n < 2; ++n) acc[a][b][m][n] = (f32x4){0.f, 0.f, 0.f, 0.f};
;         cur = nxt; cA = nA; cB = nB; ++ui;
.LBB0_666:
	s_ashr_i32 s23, s22, 31
	s_lshl_b64 s[24:25], s[22:23], 20
	s_add_u32 s24, s21, s24
	s_addc_u32 s25, s38, s25
	s_and_b64 s[28:29], s[44:45], exec
	s_cselect_b32 s23, s25, s1
	s_cselect_b32 s59, s24, s0
	s_ashr_i32 s19, s18, 31
	s_lshl_b64 s[28:29], s[18:19], 20
	s_add_u32 s28, s39, s28
	s_addc_u32 s29, s46, s29
	s_and_b64 s[36:37], s[44:45], exec
	s_cselect_b32 s19, s29, s31
	s_cselect_b32 s60, s28, s30
	s_add_u32 s0, s0, 0x80080
	s_addc_u32 s1, s1, 0
	s_add_u32 s61, s30, 0x100
	v_mov_b32_e32 v2, 0
	s_addc_u32 s62, s31, 0
	s_mov_b32 s63, -2
	v_mov_b32_e32 v3, v2
	v_mov_b32_e32 v4, v2
	v_mov_b32_e32 v5, v2
	v_mov_b32_e32 v6, v2
	v_mov_b32_e32 v7, v2
	v_mov_b32_e32 v8, v2
	v_mov_b32_e32 v9, v2
	v_mov_b32_e32 v18, v2
	v_mov_b32_e32 v19, v2
	v_mov_b32_e32 v20, v2
	v_mov_b32_e32 v21, v2
	v_mov_b32_e32 v22, v2
	v_mov_b32_e32 v23, v2
	v_mov_b32_e32 v24, v2
	v_mov_b32_e32 v25, v2
	v_mov_b32_e32 v34, v2
	v_mov_b32_e32 v35, v2
	v_mov_b32_e32 v36, v2
	v_mov_b32_e32 v37, v2
	v_mov_b32_e32 v38, v2
	v_mov_b32_e32 v39, v2
	v_mov_b32_e32 v40, v2
	v_mov_b32_e32 v41, v2
	v_mov_b32_e32 v50, v2
	v_mov_b32_e32 v51, v2
	v_mov_b32_e32 v52, v2
	v_mov_b32_e32 v53, v2
	v_mov_b32_e32 v54, v2
	v_mov_b32_e32 v55, v2
	v_mov_b32_e32 v56, v2
	v_mov_b32_e32 v57, v2
	v_mov_b32_e32 v10, v2
	v_mov_b32_e32 v11, v2
	v_mov_b32_e32 v12, v2
	v_mov_b32_e32 v13, v2
	v_mov_b32_e32 v14, v2
	v_mov_b32_e32 v15, v2
	v_mov_b32_e32 v16, v2
	v_mov_b32_e32 v17, v2
	v_mov_b32_e32 v26, v2
	v_mov_b32_e32 v27, v2
	v_mov_b32_e32 v28, v2
	v_mov_b32_e32 v29, v2
	v_mov_b32_e32 v30, v2
	v_mov_b32_e32 v31, v2
	v_mov_b32_e32 v32, v2
	v_mov_b32_e32 v33, v2
	v_mov_b32_e32 v42, v2
	v_mov_b32_e32 v43, v2
	v_mov_b32_e32 v44, v2
	v_mov_b32_e32 v45, v2
	v_mov_b32_e32 v46, v2
	v_mov_b32_e32 v47, v2
	v_mov_b32_e32 v48, v2
	v_mov_b32_e32 v49, v2
	v_mov_b32_e32 v58, v2
	v_mov_b32_e32 v59, v2
	v_mov_b32_e32 v60, v2
	v_mov_b32_e32 v61, v2
	v_mov_b32_e32 v62, v2
	v_mov_b32_e32 v63, v2
	v_mov_b32_e32 v64, v2
	v_mov_b32_e32 v65, v2
	v_mov_b32_e32 v66, v2
	v_mov_b32_e32 v67, v2
	v_mov_b32_e32 v68, v2
	v_mov_b32_e32 v69, v2
	v_mov_b32_e32 v70, v2
	v_mov_b32_e32 v71, v2
	v_mov_b32_e32 v72, v2
	v_mov_b32_e32 v73, v2
	v_mov_b32_e32 v82, v2
	v_mov_b32_e32 v83, v2
	v_mov_b32_e32 v84, v2
	v_mov_b32_e32 v85, v2
	v_mov_b32_e32 v86, v2
	v_mov_b32_e32 v87, v2
	v_mov_b32_e32 v88, v2
	v_mov_b32_e32 v89, v2
	v_mov_b32_e32 v98, v2
	v_mov_b32_e32 v99, v2
	v_mov_b32_e32 v100, v2
	v_mov_b32_e32 v101, v2
	v_mov_b32_e32 v102, v2
	v_mov_b32_e32 v103, v2
	v_mov_b32_e32 v104, v2
	v_mov_b32_e32 v105, v2
	v_mov_b32_e32 v114, v2
	v_mov_b32_e32 v115, v2
	v_mov_b32_e32 v116, v2
	v_mov_b32_e32 v117, v2
	v_mov_b32_e32 v118, v2
	v_mov_b32_e32 v119, v2
	v_mov_b32_e32 v120, v2
	v_mov_b32_e32 v121, v2
	v_mov_b32_e32 v74, v2
	v_mov_b32_e32 v75, v2
	v_mov_b32_e32 v76, v2
	v_mov_b32_e32 v77, v2
	v_mov_b32_e32 v78, v2
	v_mov_b32_e32 v79, v2
	v_mov_b32_e32 v80, v2
	v_mov_b32_e32 v81, v2
	v_mov_b32_e32 v90, v2
	v_mov_b32_e32 v91, v2
	v_mov_b32_e32 v92, v2
	v_mov_b32_e32 v93, v2
	v_mov_b32_e32 v94, v2
	v_mov_b32_e32 v95, v2
	v_mov_b32_e32 v96, v2
	v_mov_b32_e32 v97, v2
	v_mov_b32_e32 v106, v2
	v_mov_b32_e32 v107, v2
	v_mov_b32_e32 v108, v2
	v_mov_b32_e32 v109, v2
	v_mov_b32_e32 v110, v2
	v_mov_b32_e32 v111, v2
	v_mov_b32_e32 v112, v2
	v_mov_b32_e32 v113, v2
	v_mov_b32_e32 v122, v2
	v_mov_b32_e32 v123, v2
	v_mov_b32_e32 v124, v2
	v_mov_b32_e32 v125, v2
	v_mov_b32_e32 v126, v2
	v_mov_b32_e32 v127, v2
	v_mov_b32_e32 v128, v2
	v_mov_b32_e32 v129, v2
	.p2align	8

; template <class Epi, class Sched, bool ALIGN_EPI = false, bool SP2 = false>
; __device__ __forceinline__ void gemm_phase(PG8_LAS unsigned char* lds, const Gemm g, const Sched& S, const Epi& E) {
;     ...
;     for (;;) {
;         const bool has_next = S.next(ui + 1, nxt);
;         const char* nA = has_next ? (const char*)g.A + (size_t)nxt.pm * tstep : cA; const char* nB = has_next ? (const char*)g.Bt + (size_t)nxt.pn * tstep : cB;
;         for (int t = 0; t < nt; t += 2) {
;             const bool last = (t == nt - 2);
;             const char* a1 = cA + (size_t)(t + 1) * kstep;
;             const char* a2 = last ? nA : cA + (size_t)(t + 2) * kstep; const char* b2 = last ? nB : cB + (size_t)(t + 2) * kstep;
;             const char* a3 = a2 + kstep; const char* b3 = b2 + kstep;
;     ...
; #pragma unroll
;         for (int a = 0; a < 2; ++a)
; #pragma unroll
;             for (int b = 0; b < 2; ++b)
; #pragma unroll
;                 for (int m = 0; m < 4; ++m)
; #pragma unroll
;                     for (int n = 0; n < 2; ++n) acc[a][b][m][n] = (f32x4){0.f, 0.f, 0.f, 0.f};
;         cur = nxt; cA = nA; cB = nB; ++ui;
.LBB0_761:
	s_ashr_i32 s23, s22, 31
	s_lshl_b64 s[0:1], s[22:23], 20
	s_add_u32 s24, s21, s0
	s_addc_u32 s25, s34, s1
	s_and_b64 s[0:1], s[44:45], exec
	s_cselect_b32 s23, s25, s37
	s_cselect_b32 s60, s24, s36
	s_ashr_i32 s19, s18, 31
	s_lshl_b64 s[0:1], s[18:19], 20
	s_add_u32 s28, s38, s0
	s_addc_u32 s29, s39, s1
	s_and_b64 s[0:1], s[44:45], exec
	s_cselect_b32 s19, s29, s31
	s_cselect_b32 s61, s28, s30
	s_add_u32 s0, s36, 0x80080
	s_addc_u32 s1, s37, 0
	s_add_u32 s62, s30, 0x100
	v_mov_b32_e32 v2, 0
	s_addc_u32 s63, s31, 0
	s_mov_b32 s66, -2
	v_mov_b32_e32 v3, v2
	v_mov_b32_e32 v4, v2
	v_mov_b32_e32 v5, v2
	v_mov_b32_e32 v6, v2
	v_mov_b32_e32 v7, v2
	v_mov_b32_e32 v8, v2
	v_mov_b32_e32 v9, v2
	v_mov_b32_e32 v18, v2
	v_mov_b32_e32 v19, v2
	v_mov_b32_e32 v20, v2
	v_mov_b32_e32 v21, v2
	v_mov_b32_e32 v22, v2
	v_mov_b32_e32 v23, v2
	v_mov_b32_e32 v24, v2
	v_mov_b32_e32 v25, v2
	v_mov_b32_e32 v34, v2
	v_mov_b32_e32 v35, v2
	v_mov_b32_e32 v36, v2
	v_mov_b32_e32 v37, v2
	v_mov_b32_e32 v38, v2
	v_mov_b32_e32 v39, v2
	v_mov_b32_e32 v40, v2
	v_mov_b32_e32 v41, v2
	v_mov_b32_e32 v50, v2
	v_mov_b32_e32 v51, v2
	v_mov_b32_e32 v52, v2
	v_mov_b32_e32 v53, v2
	v_mov_b32_e32 v54, v2
	v_mov_b32_e32 v55, v2
	v_mov_b32_e32 v56, v2
	v_mov_b32_e32 v57, v2
	v_mov_b32_e32 v10, v2
	v_mov_b32_e32 v11, v2
	v_mov_b32_e32 v12, v2
	v_mov_b32_e32 v13, v2
	v_mov_b32_e32 v14, v2
	v_mov_b32_e32 v15, v2
	v_mov_b32_e32 v16, v2
	v_mov_b32_e32 v17, v2
	v_mov_b32_e32 v26, v2
	v_mov_b32_e32 v27, v2
	v_mov_b32_e32 v28, v2
	v_mov_b32_e32 v29, v2
	v_mov_b32_e32 v30, v2
	v_mov_b32_e32 v31, v2
	v_mov_b32_e32 v32, v2
	v_mov_b32_e32 v33, v2
	v_mov_b32_e32 v42, v2
	v_mov_b32_e32 v43, v2
	v_mov_b32_e32 v44, v2
	v_mov_b32_e32 v45, v2
	v_mov_b32_e32 v46, v2
	v_mov_b32_e32 v47, v2
	v_mov_b32_e32 v48, v2
	v_mov_b32_e32 v49, v2
	v_mov_b32_e32 v58, v2
	v_mov_b32_e32 v59, v2
	v_mov_b32_e32 v60, v2
	v_mov_b32_e32 v61, v2
	v_mov_b32_e32 v62, v2
	v_mov_b32_e32 v63, v2
	v_mov_b32_e32 v64, v2
	v_mov_b32_e32 v65, v2
	v_mov_b32_e32 v66, v2
	v_mov_b32_e32 v67, v2
	v_mov_b32_e32 v68, v2
	v_mov_b32_e32 v69, v2
	v_mov_b32_e32 v70, v2
	v_mov_b32_e32 v71, v2
	v_mov_b32_e32 v72, v2
	v_mov_b32_e32 v73, v2
	v_mov_b32_e32 v82, v2
	v_mov_b32_e32 v83, v2
	v_mov_b32_e32 v84, v2
	v_mov_b32_e32 v85, v2
	v_mov_b32_e32 v86, v2
	v_mov_b32_e32 v87, v2
	v_mov_b32_e32 v88, v2
	v_mov_b32_e32 v89, v2
	v_mov_b32_e32 v98, v2
	v_mov_b32_e32 v99, v2
	v_mov_b32_e32 v100, v2
	v_mov_b32_e32 v101, v2
	v_mov_b32_e32 v102, v2
	v_mov_b32_e32 v103, v2
	v_mov_b32_e32 v104, v2
	v_mov_b32_e32 v105, v2
	v_mov_b32_e32 v114, v2
	v_mov_b32_e32 v115, v2
	v_mov_b32_e32 v116, v2
	v_mov_b32_e32 v117, v2
	v_mov_b32_e32 v118, v2
	v_mov_b32_e32 v119, v2
	v_mov_b32_e32 v120, v2
	v_mov_b32_e32 v121, v2
	v_mov_b32_e32 v74, v2
	v_mov_b32_e32 v75, v2
	v_mov_b32_e32 v76, v2
	v_mov_b32_e32 v77, v2
	v_mov_b32_e32 v78, v2
	v_mov_b32_e32 v79, v2
	v_mov_b32_e32 v80, v2
	v_mov_b32_e32 v81, v2
	v_mov_b32_e32 v90, v2
	v_mov_b32_e32 v91, v2
	v_mov_b32_e32 v92, v2
	v_mov_b32_e32 v93, v2
	v_mov_b32_e32 v94, v2
	v_mov_b32_e32 v95, v2
	v_mov_b32_e32 v96, v2
	v_mov_b32_e32 v97, v2
	v_mov_b32_e32 v106, v2
	v_mov_b32_e32 v107, v2
	v_mov_b32_e32 v108, v2
	v_mov_b32_e32 v109, v2
	v_mov_b32_e32 v110, v2
	v_mov_b32_e32 v111, v2
	v_mov_b32_e32 v112, v2
	v_mov_b32_e32 v113, v2
	v_mov_b32_e32 v122, v2
	v_mov_b32_e32 v123, v2
	v_mov_b32_e32 v124, v2
	v_mov_b32_e32 v125, v2
	v_mov_b32_e32 v126, v2
	v_mov_b32_e32 v127, v2
	v_mov_b32_e32 v128, v2
	v_mov_b32_e32 v129, v2
	.p2align	8

; template <class Epi, class Sched, bool ALIGN_EPI = false, bool SP2 = false>
; __device__ __forceinline__ void gemm_phase(PG8_LAS unsigned char* lds, const Gemm g, const Sched& S, const Epi& E) {
;     ...
;     for (;;) {
;         const bool has_next = S.next(ui + 1, nxt);
;         const char* nA = has_next ? (const char*)g.A + (size_t)nxt.pm * tstep : cA; const char* nB = has_next ? (const char*)g.Bt + (size_t)nxt.pn * tstep : cB;
;         for (int t = 0; t < nt; t += 2) {
;             const bool last = (t == nt - 2);
;             const char* a1 = cA + (size_t)(t + 1) * kstep;
;             const char* a2 = last ? nA : cA + (size_t)(t + 2) * kstep; const char* b2 = last ? nB : cB + (size_t)(t + 2) * kstep;
;             const char* a3 = a2 + kstep; const char* b3 = b2 + kstep;
;     ...
; #pragma unroll
;         for (int a = 0; a < 2; ++a)
; #pragma unroll
;             for (int b = 0; b < 2; ++b)
; #pragma unroll
;                 for (int m = 0; m < 4; ++m)
; #pragma unroll
;                     for (int n = 0; n < 2; ++n) acc[a][b][m][n] = (f32x4){0.f, 0.f, 0.f, 0.f};
;         cur = nxt; cA = nA; cB = nB; ++ui;
.LBB0_841:
	s_ashr_i32 s23, s22, 31
	s_lshl_b64 s[24:25], s[22:23], 22
	s_add_u32 s24, s38, s24
	s_addc_u32 s25, s39, s25
	s_and_b64 s[28:29], s[44:45], exec
	s_cselect_b32 s23, s25, s1
	s_cselect_b32 s61, s24, s0
	s_ashr_i32 s19, s18, 31
	s_lshl_b64 s[28:29], s[18:19], 22
	s_add_u32 s28, s48, s28
	s_addc_u32 s29, s49, s29
	s_and_b64 s[36:37], s[44:45], exec
	s_cselect_b32 s19, s29, s31
	s_cselect_b32 s62, s28, s30
	s_add_u32 s0, s0, 0x200080
	s_addc_u32 s1, s1, 0
	s_add_u32 s63, s30, 0x100
	v_mov_b32_e32 v2, 0
	s_addc_u32 s66, s31, 0
	s_mov_b32 s67, -2
	v_mov_b32_e32 v3, v2
	v_mov_b32_e32 v4, v2
	v_mov_b32_e32 v5, v2
	v_mov_b32_e32 v6, v2
	v_mov_b32_e32 v7, v2
	v_mov_b32_e32 v8, v2
	v_mov_b32_e32 v9, v2
	v_mov_b32_e32 v18, v2
	v_mov_b32_e32 v19, v2
	v_mov_b32_e32 v20, v2
	v_mov_b32_e32 v21, v2
	v_mov_b32_e32 v22, v2
	v_mov_b32_e32 v23, v2
	v_mov_b32_e32 v24, v2
	v_mov_b32_e32 v25, v2
	v_mov_b32_e32 v34, v2
	v_mov_b32_e32 v35, v2
	v_mov_b32_e32 v36, v2
	v_mov_b32_e32 v37, v2
	v_mov_b32_e32 v38, v2
	v_mov_b32_e32 v39, v2
	v_mov_b32_e32 v40, v2
	v_mov_b32_e32 v41, v2
	v_mov_b32_e32 v50, v2
	v_mov_b32_e32 v51, v2
	v_mov_b32_e32 v52, v2
	v_mov_b32_e32 v53, v2
	v_mov_b32_e32 v54, v2
	v_mov_b32_e32 v55, v2
	v_mov_b32_e32 v56, v2
	v_mov_b32_e32 v57, v2
	v_mov_b32_e32 v10, v2
	v_mov_b32_e32 v11, v2
	v_mov_b32_e32 v12, v2
	v_mov_b32_e32 v13, v2
	v_mov_b32_e32 v14, v2
	v_mov_b32_e32 v15, v2
	v_mov_b32_e32 v16, v2
	v_mov_b32_e32 v17, v2
	v_mov_b32_e32 v26, v2
	v_mov_b32_e32 v27, v2
	v_mov_b32_e32 v28, v2
	v_mov_b32_e32 v29, v2
	v_mov_b32_e32 v30, v2
	v_mov_b32_e32 v31, v2
	v_mov_b32_e32 v32, v2
	v_mov_b32_e32 v33, v2
	v_mov_b32_e32 v42, v2
	v_mov_b32_e32 v43, v2
	v_mov_b32_e32 v44, v2
	v_mov_b32_e32 v45, v2
	v_mov_b32_e32 v46, v2
	v_mov_b32_e32 v47, v2
	v_mov_b32_e32 v48, v2
	v_mov_b32_e32 v49, v2
	v_mov_b32_e32 v58, v2
	v_mov_b32_e32 v59, v2
	v_mov_b32_e32 v60, v2
	v_mov_b32_e32 v61, v2
	v_mov_b32_e32 v62, v2
	v_mov_b32_e32 v63, v2
	v_mov_b32_e32 v64, v2
	v_mov_b32_e32 v65, v2
	v_mov_b32_e32 v66, v2
	v_mov_b32_e32 v67, v2
	v_mov_b32_e32 v68, v2
	v_mov_b32_e32 v69, v2
	v_mov_b32_e32 v70, v2
	v_mov_b32_e32 v71, v2
	v_mov_b32_e32 v72, v2
	v_mov_b32_e32 v73, v2
	v_mov_b32_e32 v82, v2
	v_mov_b32_e32 v83, v2
	v_mov_b32_e32 v84, v2
	v_mov_b32_e32 v85, v2
	v_mov_b32_e32 v86, v2
	v_mov_b32_e32 v87, v2
	v_mov_b32_e32 v88, v2
	v_mov_b32_e32 v89, v2
	v_mov_b32_e32 v98, v2
	v_mov_b32_e32 v99, v2
	v_mov_b32_e32 v100, v2
	v_mov_b32_e32 v101, v2
	v_mov_b32_e32 v102, v2
	v_mov_b32_e32 v103, v2
	v_mov_b32_e32 v104, v2
	v_mov_b32_e32 v105, v2
	v_mov_b32_e32 v114, v2
	v_mov_b32_e32 v115, v2
	v_mov_b32_e32 v116, v2
	v_mov_b32_e32 v117, v2
	v_mov_b32_e32 v118, v2
	v_mov_b32_e32 v119, v2
	v_mov_b32_e32 v120, v2
	v_mov_b32_e32 v121, v2
	v_mov_b32_e32 v74, v2
	v_mov_b32_e32 v75, v2
	v_mov_b32_e32 v76, v2
	v_mov_b32_e32 v77, v2
	v_mov_b32_e32 v78, v2
	v_mov_b32_e32 v79, v2
	v_mov_b32_e32 v80, v2
	v_mov_b32_e32 v81, v2
	v_mov_b32_e32 v90, v2
	v_mov_b32_e32 v91, v2
	v_mov_b32_e32 v92, v2
	v_mov_b32_e32 v93, v2
	v_mov_b32_e32 v94, v2
	v_mov_b32_e32 v95, v2
	v_mov_b32_e32 v96, v2
	v_mov_b32_e32 v97, v2
	v_mov_b32_e32 v106, v2
	v_mov_b32_e32 v107, v2
	v_mov_b32_e32 v108, v2
	v_mov_b32_e32 v109, v2
	v_mov_b32_e32 v110, v2
	v_mov_b32_e32 v111, v2
	v_mov_b32_e32 v112, v2
	v_mov_b32_e32 v113, v2
	v_mov_b32_e32 v122, v2
	v_mov_b32_e32 v123, v2
	v_mov_b32_e32 v124, v2
	v_mov_b32_e32 v125, v2
	v_mov_b32_e32 v126, v2
	v_mov_b32_e32 v127, v2
	v_mov_b32_e32 v128, v2
	v_mov_b32_e32 v129, v2
	.p2align	8

; template <class Epi, class Sched, bool ALIGN_EPI = false, bool SP2 = false>
; __device__ __forceinline__ void gemm_phase(PG8_LAS unsigned char* lds, const Gemm g, const Sched& S, const Epi& E) {
;     ...
;     for (;;) {
;         const bool has_next = S.next(ui + 1, nxt);
;         const char* nA = has_next ? (const char*)g.A + (size_t)nxt.pm * tstep : cA; const char* nB = has_next ? (const char*)g.Bt + (size_t)nxt.pn * tstep : cB;
;         for (int t = 0; t < nt; t += 2) {
;             const bool last = (t == nt - 2);
;             const char* a1 = cA + (size_t)(t + 1) * kstep;
;             const char* a2 = last ? nA : cA + (size_t)(t + 2) * kstep; const char* b2 = last ? nB : cB + (size_t)(t + 2) * kstep;
;             const char* a3 = a2 + kstep; const char* b3 = b2 + kstep;
;     ...
; #pragma unroll
;         for (int a = 0; a < 2; ++a)
; #pragma unroll
;             for (int b = 0; b < 2; ++b)
; #pragma unroll
;                 for (int m = 0; m < 4; ++m)
; #pragma unroll
;                     for (int n = 0; n < 2; ++n) acc[a][b][m][n] = (f32x4){0.f, 0.f, 0.f, 0.f};
;         cur = nxt; cA = nA; cB = nB; ++ui;
.LBB0_879:
	s_ashr_i32 s19, s18, 31
	s_lshl_b64 s[22:23], s[18:19], 22
	s_add_u32 s22, s38, s22
	s_addc_u32 s23, s39, s23
	s_and_b64 s[24:25], s[40:41], exec
	s_cselect_b32 s19, s23, s1
	s_cselect_b32 s54, s22, s0
	s_ashr_i32 s17, s16, 31
	s_lshl_b64 s[24:25], s[16:17], 22
	s_add_u32 s24, s48, s24
	s_addc_u32 s25, s49, s25
	s_and_b64 s[30:31], s[40:41], exec
	s_cselect_b32 s17, s25, s29
	s_cselect_b32 s55, s24, s28
	s_add_u32 s0, s0, 0x200080
	s_addc_u32 s1, s1, 0
	s_add_u32 s56, s28, 0x100
	v_mov_b32_e32 v2, 0
	s_addc_u32 s57, s29, 0
	s_mov_b32 s58, -2
	v_mov_b32_e32 v3, v2
	v_mov_b32_e32 v4, v2
	v_mov_b32_e32 v5, v2
	v_mov_b32_e32 v6, v2
	v_mov_b32_e32 v7, v2
	v_mov_b32_e32 v8, v2
	v_mov_b32_e32 v9, v2
	v_mov_b32_e32 v14, v2
	v_mov_b32_e32 v15, v2
	v_mov_b32_e32 v16, v2
	v_mov_b32_e32 v17, v2
	v_mov_b32_e32 v22, v2
	v_mov_b32_e32 v23, v2
	v_mov_b32_e32 v24, v2
	v_mov_b32_e32 v25, v2
	v_mov_b32_e32 v30, v2
	v_mov_b32_e32 v31, v2
	v_mov_b32_e32 v32, v2
	v_mov_b32_e32 v33, v2
	v_mov_b32_e32 v38, v2
	v_mov_b32_e32 v39, v2
	v_mov_b32_e32 v40, v2
	v_mov_b32_e32 v41, v2
	v_mov_b32_e32 v46, v2
	v_mov_b32_e32 v47, v2
	v_mov_b32_e32 v48, v2
	v_mov_b32_e32 v49, v2
	v_mov_b32_e32 v54, v2
	v_mov_b32_e32 v55, v2
	v_mov_b32_e32 v56, v2
	v_mov_b32_e32 v57, v2
	v_mov_b32_e32 v10, v2
	v_mov_b32_e32 v11, v2
	v_mov_b32_e32 v12, v2
	v_mov_b32_e32 v13, v2
	v_mov_b32_e32 v18, v2
	v_mov_b32_e32 v19, v2
	v_mov_b32_e32 v20, v2
	v_mov_b32_e32 v21, v2
	v_mov_b32_e32 v26, v2
	v_mov_b32_e32 v27, v2
	v_mov_b32_e32 v28, v2
	v_mov_b32_e32 v29, v2
	v_mov_b32_e32 v34, v2
	v_mov_b32_e32 v35, v2
	v_mov_b32_e32 v36, v2
	v_mov_b32_e32 v37, v2
	v_mov_b32_e32 v42, v2
	v_mov_b32_e32 v43, v2
	v_mov_b32_e32 v44, v2
	v_mov_b32_e32 v45, v2
	v_mov_b32_e32 v50, v2
	v_mov_b32_e32 v51, v2
	v_mov_b32_e32 v52, v2
	v_mov_b32_e32 v53, v2
	v_mov_b32_e32 v58, v2
	v_mov_b32_e32 v59, v2
	v_mov_b32_e32 v60, v2
	v_mov_b32_e32 v61, v2
	v_mov_b32_e32 v62, v2
	v_mov_b32_e32 v63, v2
	v_mov_b32_e32 v64, v2
	v_mov_b32_e32 v65, v2
	v_mov_b32_e32 v66, v2
	v_mov_b32_e32 v67, v2
	v_mov_b32_e32 v68, v2
	v_mov_b32_e32 v69, v2
	v_mov_b32_e32 v70, v2
	v_mov_b32_e32 v71, v2
	v_mov_b32_e32 v72, v2
	v_mov_b32_e32 v73, v2
	v_mov_b32_e32 v78, v2
	v_mov_b32_e32 v79, v2
	v_mov_b32_e32 v80, v2
	v_mov_b32_e32 v81, v2
	v_mov_b32_e32 v86, v2
	v_mov_b32_e32 v87, v2
	v_mov_b32_e32 v88, v2
	v_mov_b32_e32 v89, v2
	v_mov_b32_e32 v98, v2
	v_mov_b32_e32 v99, v2
	v_mov_b32_e32 v100, v2
	v_mov_b32_e32 v101, v2
	v_mov_b32_e32 v102, v2
	v_mov_b32_e32 v103, v2
	v_mov_b32_e32 v104, v2
	v_mov_b32_e32 v105, v2
	v_mov_b32_e32 v106, v2
	v_mov_b32_e32 v107, v2
	v_mov_b32_e32 v108, v2
	v_mov_b32_e32 v109, v2
	v_mov_b32_e32 v110, v2
	v_mov_b32_e32 v111, v2
	v_mov_b32_e32 v112, v2
	v_mov_b32_e32 v113, v2
	v_mov_b32_e32 v74, v2
	v_mov_b32_e32 v75, v2
	v_mov_b32_e32 v76, v2
	v_mov_b32_e32 v77, v2
	v_mov_b32_e32 v82, v2
	v_mov_b32_e32 v83, v2
	v_mov_b32_e32 v84, v2
	v_mov_b32_e32 v85, v2
	v_mov_b32_e32 v90, v2
	v_mov_b32_e32 v91, v2
	v_mov_b32_e32 v92, v2
	v_mov_b32_e32 v93, v2
	v_mov_b32_e32 v94, v2
	v_mov_b32_e32 v95, v2
	v_mov_b32_e32 v96, v2
	v_mov_b32_e32 v97, v2
	v_mov_b32_e32 v114, v2
	v_mov_b32_e32 v115, v2
	v_mov_b32_e32 v116, v2
	v_mov_b32_e32 v117, v2
	v_mov_b32_e32 v118, v2
	v_mov_b32_e32 v119, v2
	v_mov_b32_e32 v120, v2
	v_mov_b32_e32 v121, v2
	v_mov_b32_e32 v122, v2
	v_mov_b32_e32 v123, v2
	v_mov_b32_e32 v124, v2
	v_mov_b32_e32 v125, v2
	v_mov_b32_e32 v126, v2
	v_mov_b32_e32 v127, v2
	v_mov_b32_e32 v128, v2
	v_mov_b32_e32 v129, v2
	.p2align	8
